# forgetting-attention loop role A: staging stores and next loads between its PV and QK MFMA phases (all its fragment reads are issued, role B is still in its softmax): no LDS-write wait left in either
# speedup vs baseline: 1.0235x; 1.0235x over previous
; __device__ __forceinline__ s16x4 vtr(ldsp p) { return __builtin_bit_cast(s16x4, __builtin_amdgcn_ds_read_tr16_b64_v4i16((LAS v4i16_t*)p)); }
; #define MASK_BLOCK() do { if (kt == 0 || kt >= diag0) { \
;             _Pragma("unroll") for (int r = 0; r < 16; ++r) { const int kpp = 64 * kt + crow(r, hi); \
;                 if (kpp < 48 || kpp > q_pp) s0[r] = -INFINITY; \
;                 if (kpp + 32 < 48 || kpp + 32 > q_pp) s1[r] = -INFINITY; } } } while (0)
; #define EXPSUM_BLOCK() do { psa = 0.f; psb = 0.f; \
;             _Pragma("unroll") for (int r = 0; r < 16; ++r) { s0[r] = __builtin_amdgcn_exp2f(s0[r]); s1[r] = __builtin_amdgcn_exp2f(s1[r]); psa += s0[r]; asm("" : "+v"(psa)); psb += s1[r]; asm("" : "+v"(psb)); } } while (0)
; template <bool DIFF>
; __device__ __forceinline__ void attn_unit(const AttnP& A, int b, int h, int qi, ldsp lds) {
;     ...
;     for (int kt = kt0; kt < nt; ++kt) {
;         if (kt + 1 < nt) LOAD_TILE(kt + 1);
;         if (64 * kt <= qmax_w) {
;             ldsp Kb = lds + (kt & 1) * STAGE; ldsp Vb = Kb + 64 * KP;
;             bf16x8 kf[8]; bf16x8 ka0, ka1, qa; f32x16 s0, s1;
;     ...
;             QK_BLOCK();
;             s16x4 vlo[8], vhi[8];
; #pragma unroll
;             for (int t = 0; t < 2; ++t)
; #pragma unroll
;                 for (int j = 0; j < 4; ++j) { vlo[t * 4 + j] = vtr(Vb + trb + (16 * j) * VP + t * 64); vhi[t * 4 + j] = vtr(Vb + trb + (16 * j + 8) * VP + t * 64); }
;             __builtin_amdgcn_sched_barrier(0);
;             MASK_BLOCK();
;             bool full = (kt == kt0);
;             float psa, psb;
;             if (!full) {
;                 EXPSUM_BLOCK();
;                 if (__any(psa + psb > 1.0e18f)) { full = true; QK_BLOCK();
.Lfa_s_top:
	s_bitcmp1_b32 s99, 0
	s_cselect_b32 s74, 0x5500, 0
	s_sub_i32 s75, 0x5500, s74
	v_add_u32_e32 v169, s74, v150
	v_add_u32_e32 v0, s74, v164
	v_add_u32_e32 v168, s75, v161
	ds_read_b64_tr_b16 v[106:107], v168 offset:9216
	ds_read_b64_tr_b16 v[108:109], v168 offset:10752
	ds_read_b64_tr_b16 v[110:111], v168 offset:9280
	ds_read_b64_tr_b16 v[112:113], v168 offset:10816
	ds_read_b64_tr_b16 v[116:117], v168 offset:12288
	ds_read_b64_tr_b16 v[118:119], v168 offset:13824
	ds_read_b64_tr_b16 v[120:121], v168 offset:12352
	ds_read_b64_tr_b16 v[122:123], v168 offset:13888
	ds_read_b64_tr_b16 v[124:125], v168 offset:15360
	ds_read_b64_tr_b16 v[126:127], v168 offset:16896
	ds_read_b64_tr_b16 v[128:129], v168 offset:15424
	ds_read_b64_tr_b16 v[130:131], v168 offset:16960
	ds_read_b64_tr_b16 v[132:133], v168 offset:18432
	ds_read_b64_tr_b16 v[134:135], v168 offset:19968
	ds_read_b64_tr_b16 v[136:137], v168 offset:18496
	ds_read_b64_tr_b16 v[138:139], v168 offset:20032
	v_mov_b32_e32 v248, s97
	ds_read_b32 v248, v248
	ds_read_b128 v[170:173], v169
	ds_read_b128 v[244:247], v169 offset:4608
	s_waitcnt lgkmcnt(15)
	v_mfma_f32_32x32x16_bf16 v[18:33], v[106:109], v[66:69], v[18:33]
	ds_read_b128 v[106:109], v169 offset:32
	s_waitcnt lgkmcnt(15)
	v_mfma_f32_32x32x16_bf16 v[2:17], v[110:113], v[66:69], v[2:17]
	ds_read_b128 v[110:113], v169 offset:4640
	s_waitcnt lgkmcnt(15)
	v_mfma_f32_32x32x16_bf16 v[18:33], v[116:119], v[70:73], v[18:33]
	ds_read_b128 v[116:119], v169 offset:64
	s_waitcnt lgkmcnt(14)
	v_mfma_f32_32x32x16_bf16 v[2:17], v[120:123], v[70:73], v[2:17]
	ds_read_b128 v[120:123], v169 offset:4672
	s_waitcnt lgkmcnt(13)
	v_mfma_f32_32x32x16_bf16 v[18:33], v[124:127], v[50:53], v[18:33]
	ds_read_b128 v[124:127], v169 offset:96
	s_waitcnt lgkmcnt(12)
	v_mfma_f32_32x32x16_bf16 v[2:17], v[128:131], v[50:53], v[2:17]
	ds_read_b128 v[128:131], v169 offset:4704
	s_waitcnt lgkmcnt(11)
	v_mfma_f32_32x32x16_bf16 v[18:33], v[132:135], v[54:57], v[18:33]
	ds_read_b128 v[132:135], v0 offset:128
	s_waitcnt lgkmcnt(10)
	v_mfma_f32_32x32x16_bf16 v[2:17], v[136:139], v[54:57], v[2:17]
	ds_read_b128 v[136:139], v0 offset:4736
	s_waitcnt vmcnt(0)
	v_add_u32_e32 v115, s75, v156
	ds_write_b128 v115, v[98:101]
	s_and_saveexec_b64 s[0:1], s[44:45]
	v_xor_b32_e32 v0, 0x80000000, v155
	v_cvt_pk_bf16_f32 v0, v0, 0
	v_lshlrev_b32_e32 v249, 16, v0
	v_sub_f32_e64 v249, -v155, v249
	v_cvt_pk_bf16_f32 v162, v249, 0
	v_lshlrev_b32_e32 v162, 16, v162
	v_sub_f32_e32 v249, v249, v162
	v_cvt_pk_bf16_f32 v249, v249, 0
	v_and_or_b32 v98, v0, s83, v162
	v_and_or_b32 v99, v249, s83, 1.0
	v_mov_b32_e32 v100, v114
	v_mov_b32_e32 v101, v1
	v_add_u32_e32 v0, s75, v159
	ds_write_b128 v0, v[98:101] offset:128
	s_mov_b64 exec, s[0:1]
	v_add_u32_e32 v115, s74, v158
	ds_write_b128 v115, v[102:105] offset:9216
	global_load_dwordx4 v[102:105], v[250:251], off
	v_lshl_add_u64 v[250:251], v[250:251], 0, s[26:27]
	global_load_dwordx4 v[98:101], v[152:153], off
	v_lshl_add_u64 v[152:153], v[152:153], 0, s[26:27]
	s_and_saveexec_b64 s[0:1], s[44:45]
	global_load_dword v155, v[252:253], off
	s_mov_b64 exec, s[0:1]
	s_mov_b64 s[0:1], 0x800
	v_lshl_add_u64 v[252:253], v[252:253], 0, s[0:1]
	s_waitcnt lgkmcnt(12)
	v_mfma_f32_32x32x16_bf16 v[66:81], v[170:173], v[90:93], v[34:49]
	s_waitcnt lgkmcnt(11)
	v_mfma_f32_32x32x16_bf16 v[50:65], v[244:247], v[90:93], v[34:49]
	v_sub_f32_e32 v249, v160, v248
	v_cvt_pk_bf16_f32 v162, v249, 0
	v_lshlrev_b32_e32 v162, 16, v162
	s_waitcnt lgkmcnt(10)
	v_mfma_f32_32x32x16_bf16 v[66:81], v[106:109], v[82:85], v[66:81]
	s_waitcnt lgkmcnt(9)
	v_mfma_f32_32x32x16_bf16 v[50:65], v[110:113], v[82:85], v[50:65]
	v_sub_f32_e32 v249, v249, v162
	v_cvt_pk_bf16_f32 v163, v249, 0
	v_and_b32_e32 v157, 0xffff, v163
	v_lshlrev_b32_e32 v163, 16, v163
	s_waitcnt lgkmcnt(8)
	v_mfma_f32_32x32x16_bf16 v[66:81], v[116:119], v[86:89], v[66:81]
	s_waitcnt lgkmcnt(7)
	v_mfma_f32_32x32x16_bf16 v[50:65], v[120:123], v[86:89], v[50:65]
	v_sub_f32_e32 v249, v249, v163
	v_cvt_pk_bf16_f32 v249, v249, 0
	v_or_b32_e32 v162, 0x3f80, v162
	v_lshl_or_b32 v249, v249, 16, v157
	v_cndmask_b32_e64 v140, 0, v114, s[46:47]
	v_cndmask_b32_e64 v142, 0, v249, s[46:47]
	v_cndmask_b32_e64 v141, 0, v162, s[46:47]
	v_mov_b32_e32 v143, v1
	s_waitcnt lgkmcnt(6)
	v_mfma_f32_32x32x16_bf16 v[66:81], v[124:127], v[94:97], v[66:81]
	s_waitcnt lgkmcnt(5)
	v_mfma_f32_32x32x16_bf16 v[50:65], v[128:131], v[94:97], v[50:65]
	s_waitcnt lgkmcnt(4)
	v_mfma_f32_32x32x16_bf16 v[66:81], v[132:135], v[140:143], v[66:81]
	s_waitcnt lgkmcnt(3)
	v_mfma_f32_32x32x16_bf16 v[50:65], v[136:139], v[140:143], v[50:65]
	s_nop 7
	s_nop 3
	v_exp_f32_e32 v106, v66
	v_exp_f32_e32 v124, v50
	v_exp_f32_e32 v107, v67
	v_exp_f32_e32 v125, v51
	v_add_f32_e32 v166, 0, v106
	v_add_f32_e32 v167, 0, v124
	v_exp_f32_e32 v108, v68
	v_exp_f32_e32 v126, v52
	v_add_f32_e32 v166, v107, v166
	v_add_f32_e32 v167, v125, v167
	v_exp_f32_e32 v109, v69
	v_exp_f32_e32 v127, v53
	v_add_f32_e32 v166, v108, v166
	v_add_f32_e32 v167, v126, v167
	v_exp_f32_e32 v110, v70
	v_exp_f32_e32 v128, v54
	v_add_f32_e32 v166, v109, v166
	v_add_f32_e32 v167, v127, v167
	v_exp_f32_e32 v111, v71
	v_exp_f32_e32 v129, v55
	v_add_f32_e32 v166, v110, v166
	v_add_f32_e32 v167, v128, v167
	v_exp_f32_e32 v112, v72
	v_exp_f32_e32 v130, v56
	v_add_f32_e32 v166, v111, v166
	v_add_f32_e32 v167, v129, v167
	v_exp_f32_e32 v113, v73
	v_exp_f32_e32 v131, v57
	v_add_f32_e32 v166, v112, v166
	v_add_f32_e32 v167, v130, v167
	v_exp_f32_e32 v116, v74
	v_exp_f32_e32 v132, v58
	v_add_f32_e32 v166, v113, v166
	v_add_f32_e32 v167, v131, v167
	v_exp_f32_e32 v117, v75
	v_exp_f32_e32 v133, v59
	v_add_f32_e32 v166, v116, v166
	v_add_f32_e32 v167, v132, v167
	v_exp_f32_e32 v118, v76
	v_exp_f32_e32 v134, v60
	v_add_f32_e32 v166, v117, v166
	v_add_f32_e32 v167, v133, v167
	v_exp_f32_e32 v119, v77
	v_exp_f32_e32 v135, v61
	v_add_f32_e32 v166, v118, v166
	v_add_f32_e32 v167, v134, v167
	v_exp_f32_e32 v120, v78
	v_exp_f32_e32 v136, v62
	v_add_f32_e32 v166, v119, v166
	v_add_f32_e32 v167, v135, v167
	v_exp_f32_e32 v121, v79
	v_exp_f32_e32 v137, v63
	v_add_f32_e32 v166, v120, v166
	v_add_f32_e32 v167, v136, v167
	v_exp_f32_e32 v122, v80
	v_exp_f32_e32 v138, v64
	v_add_f32_e32 v166, v121, v166
	v_add_f32_e32 v167, v137, v167
	v_exp_f32_e32 v123, v81
	v_exp_f32_e32 v139, v65
	v_add_f32_e32 v166, v122, v166
	v_add_f32_e32 v167, v138, v167
	s_nop 0
	v_add_f32_e32 v166, v123, v166
	v_add_f32_e32 v167, v139, v167
	v_add_f32_e32 v141, v166, v167
	v_cmp_lt_f32_e32 vcc, s85, v141
	s_cbranch_vccnz .Lfa_s_slow
; __device__ __forceinline__ s16x4 vtr(ldsp p) { return __builtin_bit_cast(s16x4, __builtin_amdgcn_ds_read_tr16_b64_v4i16((LAS v4i16_t*)p)); }
; template <bool DIFF>
; __device__ __forceinline__ void attn_unit(const AttnP& A, int b, int h, int qi, ldsp lds) {
;     ...
;             l_run += psa + psb;
;     ...
;             bf16x8 pw[4];
; #pragma unroll
;             for (int j = 0; j < 4; ++j) {
;                 u32x4 pk;
;                 if (j < 2) { const int rb = 8 * (j & 1); pk.x = cvtpk(s0[rb], s0[rb + 1]); pk.y = cvtpk(s0[rb + 2], s0[rb + 3]); pk.z = cvtpk(s0[rb + 4], s0[rb + 5]); pk.w = cvtpk(s0[rb + 6], s0[rb + 7]); }
;                 else { const int rb = 8 * (j & 1); pk.x = cvtpk(s1[rb], s1[rb + 1]); pk.y = cvtpk(s1[rb + 2], s1[rb + 3]); pk.z = cvtpk(s1[rb + 4], s1[rb + 5]); pk.w = cvtpk(s1[rb + 6], s1[rb + 7]); }
;                 pw[j] = __builtin_bit_cast(bf16x8, pk);
;             }
;             __builtin_amdgcn_sched_barrier(0);
;             __builtin_amdgcn_s_setprio(1);
; #pragma unroll
;             for (int t = 0; t < 2; ++t)
; #pragma unroll
;                 for (int j = 0; j < 4; ++j) {
;                     const bf16x8 vf = (bf16x8){vlo[t * 4 + j][0], vlo[t * 4 + j][1], vlo[t * 4 + j][2], vlo[t * 4 + j][3], vhi[t * 4 + j][0], vhi[t * 4 + j][1], vhi[t * 4 + j][2], vhi[t * 4 + j][3]};
;                     o[t] = __builtin_amdgcn_mfma_f32_32x32x16_bf16(vf, pw[j], o[t], 0, 0, 0);
;                 }
;             if (DIFF) {
; #pragma unroll
;                 for (int t = 2; t < NTD; ++t)
; #pragma unroll
;                     for (int j = 0; j < 4; ++j) { vlo[(t - 2) * 4 + j] = vtr(Vb + trb + (16 * j) * VP + t * 64); vhi[(t - 2) * 4 + j] = vtr(Vb + trb + (16 * j + 8) * VP + t * 64); }
;                 __builtin_amdgcn_sched_barrier(0);
; #pragma unroll
;                 for (int t = 2; t < NTD; ++t)
; #pragma unroll
;                     for (int j = 0; j < 4; ++j) {
;                         const int i = (t - 2) * 4 + j;
;                         const bf16x8 vf = (bf16x8){vlo[i][0], vlo[i][1], vlo[i][2], vlo[i][3], vhi[i][0], vhi[i][1], vhi[i][2], vhi[i][3]};
;                         o[t] = __builtin_amdgcn_mfma_f32_32x32x16_bf16(vf, pw[j], o[t], 0, 0, 0);
;                     }
;             }
;             __builtin_amdgcn_s_setprio(0);
;         }
;         if (kt + 1 < nt) STORE_TILE((kt + 1) & 1);
;         __syncthreads();
;     }
	v_cvt_pk_bf16_f32 v66, v106, v107
	v_cvt_pk_bf16_f32 v67, v108, v109
	v_cvt_pk_bf16_f32 v68, v110, v111
	v_cvt_pk_bf16_f32 v69, v112, v113
	v_cvt_pk_bf16_f32 v70, v116, v117
	v_cvt_pk_bf16_f32 v71, v118, v119
	v_cvt_pk_bf16_f32 v72, v120, v121
	v_cvt_pk_bf16_f32 v73, v122, v123
	v_cvt_pk_bf16_f32 v50, v124, v125
	v_cvt_pk_bf16_f32 v51, v126, v127
	v_cvt_pk_bf16_f32 v52, v128, v129
	v_cvt_pk_bf16_f32 v53, v130, v131
	v_cvt_pk_bf16_f32 v54, v132, v133
	v_cvt_pk_bf16_f32 v55, v134, v135
	v_cvt_pk_bf16_f32 v56, v136, v137
	v_cvt_pk_bf16_f32 v57, v138, v139
	v_add_f32_e32 v154, v141, v154
	s_waitcnt lgkmcnt(0)
	s_barrier
	s_add_i32 s99, s99, 1
	s_add_i32 s94, s94, 1
	s_add_i32 s97, s97, 4
	s_add_i32 s98, s98, 64
	s_add_i32 s0, s95, -1
	s_cmp_le_i32 s99, s0
	s_cbranch_scc1 .Lfa_s_top
